# S5-out epilogue (VALU-only): gelu polynomial as packed f32 ops (12 more v_pk_* per step, 12 fewer instructions)
# baseline (speedup 1.0000x reference)
; #define GAS __attribute__((address_space(1)))
; #define LAS __attribute__((address_space(3)))
; __device__ __forceinline__ void ph_s5_out(Frame& F) {
;     ...
; #pragma unroll 1
;         for (int s0 = 0; s0 < 64; s0 += 16) {
;             bf16x8_t bq[16];
; #pragma unroll
;             for (int e = 0; e < 16; ++e) bq[e] = *(const GAS bf16x8_t*)(ub + 512 * (s0 + e));
; #pragma unroll
;             for (int e = 0; e < 16; ++e) { const int sI = s0 + e; const bf16x8_t b = bq[e];
; #pragma unroll
;             for (int i = 0; i < 4; ++i) { const bf16x8_t a = *(const LAS bf16x8_t*)(tl + (16 * i - sI) * 16 * TP_PITCH); acc[i] = __builtin_amdgcn_mfma_f32_32x32x16_bf16(a, b, acc[i], 0, 0, 0); }
;             }
;         }
.LBB0_972:
	v_add_co_u32_e32 v210, vcc, 0x2000, v82
	s_nop 1
	v_addc_co_u32_e32 v211, vcc, 0, v83, vcc
	v_add_co_u32_e32 v212, vcc, 0x4000, v82
	s_nop 1
	v_addc_co_u32_e32 v213, vcc, 0, v83, vcc
	ds_read_b128 v[84:87], v68 offset:11520
	ds_read_b128 v[96:99], v68 offset:12288
	s_waitcnt vmcnt(15) lgkmcnt(1)
	v_mfma_f32_32x32x16_bf16 v[50:65], v[84:87], v[142:145], v[50:65]
	ds_read_b128 v[84:87], v68 offset:23808
	ds_read_b128 v[108:111], v68 offset:24576
	s_waitcnt lgkmcnt(1)
	v_mfma_f32_32x32x16_bf16 v[34:49], v[84:87], v[142:145], v[34:49]
	ds_read_b128 v[84:87], v68 offset:36096
	ds_read_b128 v[112:115], v68 offset:36864
	s_waitcnt lgkmcnt(1)
	v_mfma_f32_32x32x16_bf16 v[18:33], v[84:87], v[142:145], v[18:33]
	ds_read_b128 v[84:87], v68 offset:48384
	ds_read_b128 v[116:119], v68
	s_waitcnt lgkmcnt(1)
	v_mfma_f32_32x32x16_bf16 v[2:17], v[84:87], v[142:145], v[2:17]
	global_load_dwordx4 v[142:145], v[82:83], off offset:1024
	ds_read_b128 v[84:87], v68 offset:10752
	ds_read_b128 v[100:103], v68 offset:9984
	s_waitcnt vmcnt(15) lgkmcnt(1)
	v_mfma_f32_32x32x16_bf16 v[50:65], v[84:87], v[146:149], v[50:65]
	ds_read_b128 v[84:87], v68 offset:23040
	ds_read_b128 v[120:123], v68 offset:22272
	s_waitcnt lgkmcnt(1)
	v_mfma_f32_32x32x16_bf16 v[34:49], v[84:87], v[146:149], v[34:49]
	ds_read_b128 v[84:87], v68 offset:35328
	ds_read_b128 v[124:127], v68 offset:34560
	ds_read_b128 v[128:131], v68 offset:46848
	s_waitcnt lgkmcnt(2)
	v_mfma_f32_32x32x16_bf16 v[18:33], v[84:87], v[146:149], v[18:33]
	ds_read_b128 v[84:87], v68 offset:47616
	s_waitcnt lgkmcnt(0)
	v_mfma_f32_32x32x16_bf16 v[2:17], v[84:87], v[146:149], v[2:17]
	global_load_dwordx4 v[146:149], v[82:83], off offset:2048
	s_waitcnt vmcnt(15)
	v_mfma_f32_32x32x16_bf16 v[50:65], v[100:103], v[150:153], v[50:65]
	v_mfma_f32_32x32x16_bf16 v[34:49], v[120:123], v[150:153], v[34:49]
	ds_read_b128 v[100:103], v68 offset:9216
	ds_read_b128 v[120:123], v68 offset:8448
	v_mfma_f32_32x32x16_bf16 v[18:33], v[124:127], v[150:153], v[18:33]
	v_mfma_f32_32x32x16_bf16 v[2:17], v[128:131], v[150:153], v[2:17]
	global_load_dwordx4 v[150:153], v[82:83], off offset:3072
	s_waitcnt vmcnt(15) lgkmcnt(1)
	v_mfma_f32_32x32x16_bf16 v[50:65], v[100:103], v[154:157], v[50:65]
	ds_read_b128 v[100:103], v68 offset:21504
	ds_read_b128 v[128:131], v68 offset:20736
	s_waitcnt lgkmcnt(1)
	v_mfma_f32_32x32x16_bf16 v[34:49], v[100:103], v[154:157], v[34:49]
	ds_read_b128 v[100:103], v68 offset:33792
	ds_read_b128 v[132:135], v68 offset:33024
	s_waitcnt lgkmcnt(1)
	v_mfma_f32_32x32x16_bf16 v[18:33], v[100:103], v[154:157], v[18:33]
	ds_read_b128 v[100:103], v68 offset:46080
	ds_read_b128 v[136:139], v68 offset:45312
	s_waitcnt lgkmcnt(1)
	v_mfma_f32_32x32x16_bf16 v[2:17], v[100:103], v[154:157], v[2:17]
	global_load_dwordx4 v[154:157], v[210:211], off offset:-4096
	s_waitcnt vmcnt(15)
	v_mfma_f32_32x32x16_bf16 v[50:65], v[120:123], v[158:161], v[50:65]
	ds_read_b128 v[100:103], v68 offset:7680
	ds_read_b128 v[120:123], v68 offset:6912
	v_mfma_f32_32x32x16_bf16 v[34:49], v[128:131], v[158:161], v[34:49]
	v_mfma_f32_32x32x16_bf16 v[18:33], v[132:135], v[158:161], v[18:33]
	s_waitcnt lgkmcnt(2)
	v_mfma_f32_32x32x16_bf16 v[2:17], v[136:139], v[158:161], v[2:17]
	global_load_dwordx4 v[158:161], v[210:211], off offset:-3072
	s_waitcnt vmcnt(15) lgkmcnt(1)
	v_mfma_f32_32x32x16_bf16 v[50:65], v[100:103], v[162:165], v[50:65]
	ds_read_b128 v[100:103], v68 offset:19968
	ds_read_b128 v[128:131], v68 offset:19200
	s_waitcnt lgkmcnt(1)
	v_mfma_f32_32x32x16_bf16 v[34:49], v[100:103], v[162:165], v[34:49]
	ds_read_b128 v[100:103], v68 offset:32256
	ds_read_b128 v[132:135], v68 offset:31488
	s_waitcnt lgkmcnt(1)
	v_mfma_f32_32x32x16_bf16 v[18:33], v[100:103], v[162:165], v[18:33]
	ds_read_b128 v[100:103], v68 offset:44544
	ds_read_b128 v[136:139], v68 offset:43776
	s_waitcnt lgkmcnt(1)
	v_mfma_f32_32x32x16_bf16 v[2:17], v[100:103], v[162:165], v[2:17]
	global_load_dwordx4 v[162:165], v[210:211], off offset:-2048
	s_waitcnt vmcnt(15)
	v_mfma_f32_32x32x16_bf16 v[50:65], v[120:123], v[166:169], v[50:65]
	ds_read_b128 v[100:103], v68 offset:6144
	ds_read_b128 v[120:123], v68 offset:5376
	v_mfma_f32_32x32x16_bf16 v[34:49], v[128:131], v[166:169], v[34:49]
	v_mfma_f32_32x32x16_bf16 v[18:33], v[132:135], v[166:169], v[18:33]
	s_waitcnt lgkmcnt(2)
	v_mfma_f32_32x32x16_bf16 v[2:17], v[136:139], v[166:169], v[2:17]
	global_load_dwordx4 v[166:169], v[210:211], off offset:-1024
	s_waitcnt vmcnt(15) lgkmcnt(1)
	v_mfma_f32_32x32x16_bf16 v[50:65], v[100:103], v[170:173], v[50:65]
	ds_read_b128 v[100:103], v68 offset:18432
	ds_read_b128 v[124:127], v68 offset:17664
	s_waitcnt lgkmcnt(1)
	v_mfma_f32_32x32x16_bf16 v[34:49], v[100:103], v[170:173], v[34:49]
	ds_read_b128 v[100:103], v68 offset:30720
	ds_read_b128 v[128:131], v68 offset:29952
	s_waitcnt lgkmcnt(1)
	v_mfma_f32_32x32x16_bf16 v[18:33], v[100:103], v[170:173], v[18:33]
	ds_read_b128 v[100:103], v68 offset:43008
	ds_read_b128 v[132:135], v68 offset:42240
	s_waitcnt lgkmcnt(1)
	v_mfma_f32_32x32x16_bf16 v[2:17], v[100:103], v[170:173], v[2:17]
	global_load_dwordx4 v[170:173], v[210:211], off offset:0
	ds_read_b128 v[84:87], v68 offset:4608
	ds_read_b128 v[100:103], v68 offset:3840
	s_waitcnt vmcnt(15)
	v_mfma_f32_32x32x16_bf16 v[50:65], v[120:123], v[174:177], v[50:65]
	v_mfma_f32_32x32x16_bf16 v[34:49], v[124:127], v[174:177], v[34:49]
	v_mfma_f32_32x32x16_bf16 v[18:33], v[128:131], v[174:177], v[18:33]
	s_waitcnt lgkmcnt(2)
	v_mfma_f32_32x32x16_bf16 v[2:17], v[132:135], v[174:177], v[2:17]
	global_load_dwordx4 v[174:177], v[210:211], off offset:1024
	s_waitcnt vmcnt(15) lgkmcnt(1)
; #define GAS __attribute__((address_space(1)))
; #define LAS __attribute__((address_space(3)))
; __device__ __forceinline__ void ph_s5_out(Frame& F) {
;     ...
; #pragma unroll 1
;         for (int s0 = 0; s0 < 64; s0 += 16) {
;             bf16x8_t bq[16];
; #pragma unroll
;             for (int e = 0; e < 16; ++e) bq[e] = *(const GAS bf16x8_t*)(ub + 512 * (s0 + e));
; #pragma unroll
;             for (int e = 0; e < 16; ++e) { const int sI = s0 + e; const bf16x8_t b = bq[e];
; #pragma unroll
;             for (int i = 0; i < 4; ++i) { const bf16x8_t a = *(const LAS bf16x8_t*)(tl + (16 * i - sI) * 16 * TP_PITCH); acc[i] = __builtin_amdgcn_mfma_f32_32x32x16_bf16(a, b, acc[i], 0, 0, 0); }
;             }
;         }
;         { const bf16* sb = (const bf16*)(ws + WS_SIN) + (size_t)g * 9 * 16 * 512 + ((size_t)nb * 16 * 64 + lane) * 8;
;           const bf16* wc = (const bf16*)(ws + WS_WC) + (size_t)g * 1024 * 256 + (((size_t)wave * 16) * 64 + lane) * 8;
; #pragma unroll 4
;           for (int kk = 0; kk < 16; ++kk) {
;               const bf16x8_t b = *(const GAS bf16x8_t*)(sb + 512 * kk);
; #pragma unroll
;               for (int i = 0; i < 4; ++i) { const bf16x8_t a = *(const GAS bf16x8_t*)(wc + (size_t)(8 * i) * 16 * 512 + 512 * kk); acc[i] = __builtin_amdgcn_mfma_f32_32x32x16_bf16(a, b, acc[i], 0, 0, 0); }
;           } }
	v_mfma_f32_32x32x16_bf16 v[50:65], v[84:87], v[178:181], v[50:65]
	ds_read_b128 v[84:87], v68 offset:16896
	ds_read_b128 v[124:127], v68 offset:16128
	s_waitcnt lgkmcnt(1)
	v_mfma_f32_32x32x16_bf16 v[34:49], v[84:87], v[178:181], v[34:49]
	ds_read_b128 v[84:87], v68 offset:29184
	ds_read_b128 v[128:131], v68 offset:28416
	s_waitcnt lgkmcnt(1)
	v_mfma_f32_32x32x16_bf16 v[18:33], v[84:87], v[178:181], v[18:33]
	ds_read_b128 v[84:87], v68 offset:41472
	ds_read_b128 v[132:135], v68 offset:40704
	s_waitcnt lgkmcnt(1)
	v_mfma_f32_32x32x16_bf16 v[2:17], v[84:87], v[178:181], v[2:17]
	global_load_dwordx4 v[178:181], v[210:211], off offset:2048
	s_waitcnt vmcnt(15)
	v_mfma_f32_32x32x16_bf16 v[50:65], v[100:103], v[182:185], v[50:65]
	v_mfma_f32_32x32x16_bf16 v[34:49], v[124:127], v[182:185], v[34:49]
	v_mfma_f32_32x32x16_bf16 v[18:33], v[128:131], v[182:185], v[18:33]
	s_waitcnt lgkmcnt(0)
	v_mfma_f32_32x32x16_bf16 v[2:17], v[132:135], v[182:185], v[2:17]
	global_load_dwordx4 v[182:185], v[210:211], off offset:3072
	ds_read_b128 v[104:107], v68 offset:3072
	ds_read_b128 v[120:123], v68 offset:2304
	s_waitcnt vmcnt(15) lgkmcnt(1)
	v_mfma_f32_32x32x16_bf16 v[50:65], v[104:107], v[190:193], v[50:65]
	ds_read_b128 v[104:107], v68 offset:15360
	ds_read_b128 v[124:127], v68 offset:14592
	s_waitcnt lgkmcnt(1)
	v_mfma_f32_32x32x16_bf16 v[34:49], v[104:107], v[190:193], v[34:49]
	ds_read_b128 v[104:107], v68 offset:27648
	ds_read_b128 v[128:131], v68 offset:26880
	s_waitcnt lgkmcnt(1)
	v_mfma_f32_32x32x16_bf16 v[18:33], v[104:107], v[190:193], v[18:33]
	ds_read_b128 v[104:107], v68 offset:39936
	ds_read_b128 v[132:135], v68 offset:39168
	s_waitcnt lgkmcnt(1)
	v_mfma_f32_32x32x16_bf16 v[2:17], v[104:107], v[190:193], v[2:17]
	global_load_dwordx4 v[190:193], v[212:213], off offset:-4096
	s_waitcnt vmcnt(15)
	v_mfma_f32_32x32x16_bf16 v[50:65], v[120:123], v[194:197], v[50:65]
	v_mfma_f32_32x32x16_bf16 v[34:49], v[124:127], v[194:197], v[34:49]
	v_mfma_f32_32x32x16_bf16 v[18:33], v[128:131], v[194:197], v[18:33]
	s_waitcnt lgkmcnt(0)
	v_mfma_f32_32x32x16_bf16 v[2:17], v[132:135], v[194:197], v[2:17]
	global_load_dwordx4 v[194:197], v[212:213], off offset:-3072
	ds_read_b128 v[100:103], v68 offset:1536
	ds_read_b128 v[120:123], v68 offset:768
	s_waitcnt vmcnt(15) lgkmcnt(1)
	v_mfma_f32_32x32x16_bf16 v[50:65], v[100:103], v[198:201], v[50:65]
	ds_read_b128 v[100:103], v68 offset:13824
	ds_read_b128 v[124:127], v68 offset:13056
	s_waitcnt lgkmcnt(1)
	v_mfma_f32_32x32x16_bf16 v[34:49], v[100:103], v[198:201], v[34:49]
	ds_read_b128 v[100:103], v68 offset:26112
	ds_read_b128 v[128:131], v68 offset:25344
	s_waitcnt lgkmcnt(1)
	v_mfma_f32_32x32x16_bf16 v[18:33], v[100:103], v[198:201], v[18:33]
	ds_read_b128 v[100:103], v68 offset:38400
	ds_read_b128 v[132:135], v68 offset:37632
	v_add_u32_e32 v68, 0xffffd000, v68
	s_waitcnt lgkmcnt(1)
	v_mfma_f32_32x32x16_bf16 v[2:17], v[100:103], v[198:201], v[2:17]
	global_load_dwordx4 v[198:201], v[212:213], off offset:-2048
	s_waitcnt vmcnt(15)
	v_mfma_f32_32x32x16_bf16 v[50:65], v[120:123], v[202:205], v[50:65]
	v_mfma_f32_32x32x16_bf16 v[34:49], v[124:127], v[202:205], v[34:49]
	v_mfma_f32_32x32x16_bf16 v[18:33], v[128:131], v[202:205], v[18:33]
	s_waitcnt lgkmcnt(0)
	v_mfma_f32_32x32x16_bf16 v[2:17], v[132:135], v[202:205], v[2:17]
	global_load_dwordx4 v[202:205], v[212:213], off offset:-1024
	s_waitcnt vmcnt(15)
	v_mfma_f32_32x32x16_bf16 v[50:65], v[116:119], v[206:209], v[50:65]
	v_mfma_f32_32x32x16_bf16 v[34:49], v[96:99], v[206:209], v[34:49]
	v_mfma_f32_32x32x16_bf16 v[18:33], v[108:111], v[206:209], v[18:33]
	v_mfma_f32_32x32x16_bf16 v[2:17], v[112:115], v[206:209], v[2:17]
	global_load_dwordx4 v[206:209], v[212:213], off offset:0
	v_lshl_add_u64 v[82:83], v[82:83], 0, s[22:23]
	s_add_i32 s25, s25, 16
	s_cmp_gt_u32 s25, 31
	s_cbranch_scc0 .LBB0_972
	s_ashr_i32 s25, s24, 31
	s_mul_i32 s49, s26, 0x24000
	s_lshl_b64 s[28:29], s[24:25], 14
	s_lshl_b64 s[34:35], s[26:27], 19
	s_mul_hi_i32 s31, s26, 0x24000
	s_add_u32 s28, s49, s28
	s_addc_u32 s29, s31, s29
	s_add_u32 s28, s28, 0x800
	s_addc_u32 s29, s29, 0
	s_add_u32 s34, s34, 0x9901000
	s_addc_u32 s35, s35, 0
	v_lshl_add_u64 v[88:89], v[80:81], 0, s[28:29]
	v_lshl_add_u64 v[214:215], v[78:79], 0, s[34:35]
	s_mov_b64 s[28:29], 0x20000
	v_lshl_add_u64 v[216:217], v[214:215], 0, s[28:29]
	v_lshl_add_u64 v[140:141], v[216:217], 0, s[28:29]
	v_lshl_add_u64 v[186:187], v[140:141], 0, s[28:29]
	ds_read_b128 v[84:87], v68 offset:11520
	ds_read_b128 v[96:99], v68 offset:12288
	s_waitcnt vmcnt(15) lgkmcnt(1)
	v_mfma_f32_32x32x16_bf16 v[50:65], v[84:87], v[142:145], v[50:65]
	ds_read_b128 v[84:87], v68 offset:23808
	ds_read_b128 v[108:111], v68 offset:24576
	s_waitcnt lgkmcnt(1)
	v_mfma_f32_32x32x16_bf16 v[34:49], v[84:87], v[142:145], v[34:49]
	ds_read_b128 v[84:87], v68 offset:36096
	ds_read_b128 v[112:115], v68 offset:36864
	s_waitcnt lgkmcnt(1)
	v_mfma_f32_32x32x16_bf16 v[18:33], v[84:87], v[142:145], v[18:33]
	ds_read_b128 v[84:87], v68 offset:48384
	ds_read_b128 v[116:119], v68
	s_waitcnt lgkmcnt(1)
	v_mfma_f32_32x32x16_bf16 v[2:17], v[84:87], v[142:145], v[2:17]
	global_load_dwordx4 v[142:145], v[88:89], off offset:-4096
	ds_read_b128 v[84:87], v68 offset:10752
	ds_read_b128 v[100:103], v68 offset:9984
	s_waitcnt vmcnt(15) lgkmcnt(1)
	v_mfma_f32_32x32x16_bf16 v[50:65], v[84:87], v[146:149], v[50:65]
	ds_read_b128 v[84:87], v68 offset:23040
	ds_read_b128 v[120:123], v68 offset:22272
	s_waitcnt lgkmcnt(1)
	v_mfma_f32_32x32x16_bf16 v[34:49], v[84:87], v[146:149], v[34:49]
	ds_read_b128 v[84:87], v68 offset:35328
	ds_read_b128 v[124:127], v68 offset:34560
	ds_read_b128 v[128:131], v68 offset:46848
	s_waitcnt lgkmcnt(2)
; #define GAS __attribute__((address_space(1)))
; #define LAS __attribute__((address_space(3)))
; __device__ __forceinline__ void ph_s5_out(Frame& F) {
;     ...
;             for (int e = 0; e < 16; ++e) bq[e] = *(const GAS bf16x8_t*)(ub + 512 * (s0 + e));
; #pragma unroll
;             for (int e = 0; e < 16; ++e) { const int sI = s0 + e; const bf16x8_t b = bq[e];
; #pragma unroll
;             for (int i = 0; i < 4; ++i) { const bf16x8_t a = *(const LAS bf16x8_t*)(tl + (16 * i - sI) * 16 * TP_PITCH); acc[i] = __builtin_amdgcn_mfma_f32_32x32x16_bf16(a, b, acc[i], 0, 0, 0); }
;             }
;         }
;         { const bf16* sb = (const bf16*)(ws + WS_SIN) + (size_t)g * 9 * 16 * 512 + ((size_t)nb * 16 * 64 + lane) * 8;
;           const bf16* wc = (const bf16*)(ws + WS_WC) + (size_t)g * 1024 * 256 + (((size_t)wave * 16) * 64 + lane) * 8;
; #pragma unroll 4
;           for (int kk = 0; kk < 16; ++kk) {
;               const bf16x8_t b = *(const GAS bf16x8_t*)(sb + 512 * kk);
; #pragma unroll
;               for (int i = 0; i < 4; ++i) { const bf16x8_t a = *(const GAS bf16x8_t*)(wc + (size_t)(8 * i) * 16 * 512 + 512 * kk); acc[i] = __builtin_amdgcn_mfma_f32_32x32x16_bf16(a, b, acc[i], 0, 0, 0); }
;           } }
	v_mfma_f32_32x32x16_bf16 v[18:33], v[84:87], v[146:149], v[18:33]
	ds_read_b128 v[84:87], v68 offset:47616
	s_waitcnt lgkmcnt(0)
	v_mfma_f32_32x32x16_bf16 v[2:17], v[84:87], v[146:149], v[2:17]
	global_load_dwordx4 v[146:149], v[214:215], off offset:-4096
	s_waitcnt vmcnt(15)
	v_mfma_f32_32x32x16_bf16 v[50:65], v[100:103], v[150:153], v[50:65]
	v_mfma_f32_32x32x16_bf16 v[34:49], v[120:123], v[150:153], v[34:49]
	ds_read_b128 v[100:103], v68 offset:9216
	ds_read_b128 v[120:123], v68 offset:8448
	v_mfma_f32_32x32x16_bf16 v[18:33], v[124:127], v[150:153], v[18:33]
	v_mfma_f32_32x32x16_bf16 v[2:17], v[128:131], v[150:153], v[2:17]
	global_load_dwordx4 v[150:153], v[216:217], off offset:-4096
	s_waitcnt vmcnt(15) lgkmcnt(1)
	v_mfma_f32_32x32x16_bf16 v[50:65], v[100:103], v[154:157], v[50:65]
	ds_read_b128 v[100:103], v68 offset:21504
	ds_read_b128 v[128:131], v68 offset:20736
	s_waitcnt lgkmcnt(1)
	v_mfma_f32_32x32x16_bf16 v[34:49], v[100:103], v[154:157], v[34:49]
	ds_read_b128 v[100:103], v68 offset:33792
	ds_read_b128 v[132:135], v68 offset:33024
	s_waitcnt lgkmcnt(1)
	v_mfma_f32_32x32x16_bf16 v[18:33], v[100:103], v[154:157], v[18:33]
	ds_read_b128 v[100:103], v68 offset:46080
	ds_read_b128 v[136:139], v68 offset:45312
	s_waitcnt lgkmcnt(1)
	v_mfma_f32_32x32x16_bf16 v[2:17], v[100:103], v[154:157], v[2:17]
	global_load_dwordx4 v[154:157], v[140:141], off offset:-4096
	s_waitcnt vmcnt(15)
	v_mfma_f32_32x32x16_bf16 v[50:65], v[120:123], v[158:161], v[50:65]
	ds_read_b128 v[100:103], v68 offset:7680
	ds_read_b128 v[120:123], v68 offset:6912
	v_mfma_f32_32x32x16_bf16 v[34:49], v[128:131], v[158:161], v[34:49]
	v_mfma_f32_32x32x16_bf16 v[18:33], v[132:135], v[158:161], v[18:33]
	s_waitcnt lgkmcnt(2)
	v_mfma_f32_32x32x16_bf16 v[2:17], v[136:139], v[158:161], v[2:17]
	global_load_dwordx4 v[158:161], v[186:187], off offset:-4096
	s_waitcnt vmcnt(15) lgkmcnt(1)
	v_mfma_f32_32x32x16_bf16 v[50:65], v[100:103], v[162:165], v[50:65]
	ds_read_b128 v[100:103], v68 offset:19968
	ds_read_b128 v[128:131], v68 offset:19200
	s_waitcnt lgkmcnt(1)
	v_mfma_f32_32x32x16_bf16 v[34:49], v[100:103], v[162:165], v[34:49]
	ds_read_b128 v[100:103], v68 offset:32256
	ds_read_b128 v[132:135], v68 offset:31488
	s_waitcnt lgkmcnt(1)
	v_mfma_f32_32x32x16_bf16 v[18:33], v[100:103], v[162:165], v[18:33]
	ds_read_b128 v[100:103], v68 offset:44544
	ds_read_b128 v[136:139], v68 offset:43776
	s_waitcnt lgkmcnt(1)
	v_mfma_f32_32x32x16_bf16 v[2:17], v[100:103], v[162:165], v[2:17]
	global_load_dwordx4 v[162:165], v[88:89], off offset:-3072
	s_waitcnt vmcnt(15)
	v_mfma_f32_32x32x16_bf16 v[50:65], v[120:123], v[166:169], v[50:65]
	ds_read_b128 v[100:103], v68 offset:6144
	ds_read_b128 v[120:123], v68 offset:5376
	v_mfma_f32_32x32x16_bf16 v[34:49], v[128:131], v[166:169], v[34:49]
	v_mfma_f32_32x32x16_bf16 v[18:33], v[132:135], v[166:169], v[18:33]
	s_waitcnt lgkmcnt(2)
	v_mfma_f32_32x32x16_bf16 v[2:17], v[136:139], v[166:169], v[2:17]
	global_load_dwordx4 v[166:169], v[214:215], off offset:-3072
	s_waitcnt vmcnt(15) lgkmcnt(1)
	v_mfma_f32_32x32x16_bf16 v[50:65], v[100:103], v[170:173], v[50:65]
	ds_read_b128 v[100:103], v68 offset:18432
	ds_read_b128 v[124:127], v68 offset:17664
	s_waitcnt lgkmcnt(1)
	v_mfma_f32_32x32x16_bf16 v[34:49], v[100:103], v[170:173], v[34:49]
	ds_read_b128 v[100:103], v68 offset:30720
	ds_read_b128 v[128:131], v68 offset:29952
	s_waitcnt lgkmcnt(1)
	v_mfma_f32_32x32x16_bf16 v[18:33], v[100:103], v[170:173], v[18:33]
	ds_read_b128 v[100:103], v68 offset:43008
	ds_read_b128 v[132:135], v68 offset:42240
	s_waitcnt lgkmcnt(1)
	v_mfma_f32_32x32x16_bf16 v[2:17], v[100:103], v[170:173], v[2:17]
	global_load_dwordx4 v[170:173], v[216:217], off offset:-3072
	ds_read_b128 v[84:87], v68 offset:4608
	ds_read_b128 v[100:103], v68 offset:3840
	s_waitcnt vmcnt(15)
	v_mfma_f32_32x32x16_bf16 v[50:65], v[120:123], v[174:177], v[50:65]
	v_mfma_f32_32x32x16_bf16 v[34:49], v[124:127], v[174:177], v[34:49]
	v_mfma_f32_32x32x16_bf16 v[18:33], v[128:131], v[174:177], v[18:33]
	s_waitcnt lgkmcnt(2)
	v_mfma_f32_32x32x16_bf16 v[2:17], v[132:135], v[174:177], v[2:17]
	global_load_dwordx4 v[174:177], v[140:141], off offset:-3072
	s_waitcnt vmcnt(15) lgkmcnt(1)
	v_mfma_f32_32x32x16_bf16 v[50:65], v[84:87], v[178:181], v[50:65]
	ds_read_b128 v[84:87], v68 offset:16896
	ds_read_b128 v[124:127], v68 offset:16128
	s_waitcnt lgkmcnt(1)
	v_mfma_f32_32x32x16_bf16 v[34:49], v[84:87], v[178:181], v[34:49]
	ds_read_b128 v[84:87], v68 offset:29184
	ds_read_b128 v[128:131], v68 offset:28416
	s_waitcnt lgkmcnt(1)
	v_mfma_f32_32x32x16_bf16 v[18:33], v[84:87], v[178:181], v[18:33]
	ds_read_b128 v[84:87], v68 offset:41472
	ds_read_b128 v[132:135], v68 offset:40704
	s_waitcnt lgkmcnt(1)
	v_mfma_f32_32x32x16_bf16 v[2:17], v[84:87], v[178:181], v[2:17]
	global_load_dwordx4 v[178:181], v[186:187], off offset:-3072
	s_waitcnt vmcnt(15)
	v_mfma_f32_32x32x16_bf16 v[50:65], v[100:103], v[182:185], v[50:65]
	v_mfma_f32_32x32x16_bf16 v[34:49], v[124:127], v[182:185], v[34:49]
	v_mfma_f32_32x32x16_bf16 v[18:33], v[128:131], v[182:185], v[18:33]
	s_waitcnt lgkmcnt(0)
	v_mfma_f32_32x32x16_bf16 v[2:17], v[132:135], v[182:185], v[2:17]
	global_load_dwordx4 v[182:185], v[88:89], off offset:-2048
	ds_read_b128 v[104:107], v68 offset:3072
	ds_read_b128 v[120:123], v68 offset:2304
	s_waitcnt vmcnt(15) lgkmcnt(1)
	v_mfma_f32_32x32x16_bf16 v[50:65], v[104:107], v[190:193], v[50:65]
	ds_read_b128 v[104:107], v68 offset:15360
	ds_read_b128 v[124:127], v68 offset:14592
	s_waitcnt lgkmcnt(1)
	v_mfma_f32_32x32x16_bf16 v[34:49], v[104:107], v[190:193], v[34:49]
	ds_read_b128 v[104:107], v68 offset:27648
	ds_read_b128 v[128:131], v68 offset:26880
	s_waitcnt lgkmcnt(1)
; #define GAS __attribute__((address_space(1)))
; __device__ __forceinline__ void ph_s5_out(Frame& F) {
;     ...
;         { const bf16* sb = (const bf16*)(ws + WS_SIN) + (size_t)g * 9 * 16 * 512 + ((size_t)nb * 16 * 64 + lane) * 8;
;           const bf16* wc = (const bf16*)(ws + WS_WC) + (size_t)g * 1024 * 256 + (((size_t)wave * 16) * 64 + lane) * 8;
; #pragma unroll 4
;           for (int kk = 0; kk < 16; ++kk) {
;               const bf16x8_t b = *(const GAS bf16x8_t*)(sb + 512 * kk);
; #pragma unroll
;               for (int i = 0; i < 4; ++i) { const bf16x8_t a = *(const GAS bf16x8_t*)(wc + (size_t)(8 * i) * 16 * 512 + 512 * kk); acc[i] = __builtin_amdgcn_mfma_f32_32x32x16_bf16(a, b, acc[i], 0, 0, 0); }
;           } }
	v_mfma_f32_32x32x16_bf16 v[18:33], v[104:107], v[190:193], v[18:33]
	ds_read_b128 v[104:107], v68 offset:39936
	ds_read_b128 v[132:135], v68 offset:39168
	s_waitcnt lgkmcnt(1)
	v_mfma_f32_32x32x16_bf16 v[2:17], v[104:107], v[190:193], v[2:17]
	global_load_dwordx4 v[190:193], v[214:215], off offset:-2048
	s_waitcnt vmcnt(15)
	v_mfma_f32_32x32x16_bf16 v[50:65], v[120:123], v[194:197], v[50:65]
	v_mfma_f32_32x32x16_bf16 v[34:49], v[124:127], v[194:197], v[34:49]
	v_mfma_f32_32x32x16_bf16 v[18:33], v[128:131], v[194:197], v[18:33]
	s_waitcnt lgkmcnt(0)
	v_mfma_f32_32x32x16_bf16 v[2:17], v[132:135], v[194:197], v[2:17]
	global_load_dwordx4 v[194:197], v[216:217], off offset:-2048
	ds_read_b128 v[100:103], v68 offset:1536
	ds_read_b128 v[120:123], v68 offset:768
	s_waitcnt vmcnt(15) lgkmcnt(1)
	v_mfma_f32_32x32x16_bf16 v[50:65], v[100:103], v[198:201], v[50:65]
	ds_read_b128 v[100:103], v68 offset:13824
	ds_read_b128 v[124:127], v68 offset:13056
	s_waitcnt lgkmcnt(1)
	v_mfma_f32_32x32x16_bf16 v[34:49], v[100:103], v[198:201], v[34:49]
	ds_read_b128 v[100:103], v68 offset:26112
	ds_read_b128 v[128:131], v68 offset:25344
	s_waitcnt lgkmcnt(1)
	v_mfma_f32_32x32x16_bf16 v[18:33], v[100:103], v[198:201], v[18:33]
	ds_read_b128 v[100:103], v68 offset:38400
	ds_read_b128 v[132:135], v68 offset:37632
	v_add_u32_e32 v68, 0xffffd000, v68
	s_waitcnt lgkmcnt(1)
	v_mfma_f32_32x32x16_bf16 v[2:17], v[100:103], v[198:201], v[2:17]
	global_load_dwordx4 v[198:201], v[140:141], off offset:-2048
	s_waitcnt vmcnt(15)
	v_mfma_f32_32x32x16_bf16 v[50:65], v[120:123], v[202:205], v[50:65]
	v_mfma_f32_32x32x16_bf16 v[34:49], v[124:127], v[202:205], v[34:49]
	v_mfma_f32_32x32x16_bf16 v[18:33], v[128:131], v[202:205], v[18:33]
	s_waitcnt lgkmcnt(0)
	v_mfma_f32_32x32x16_bf16 v[2:17], v[132:135], v[202:205], v[2:17]
	global_load_dwordx4 v[202:205], v[186:187], off offset:-2048
	s_waitcnt vmcnt(15)
	v_mfma_f32_32x32x16_bf16 v[50:65], v[116:119], v[206:209], v[50:65]
	v_mfma_f32_32x32x16_bf16 v[34:49], v[96:99], v[206:209], v[34:49]
	v_mfma_f32_32x32x16_bf16 v[18:33], v[108:111], v[206:209], v[18:33]
	v_mfma_f32_32x32x16_bf16 v[2:17], v[112:115], v[206:209], v[2:17]
	global_load_dwordx4 v[206:209], v[88:89], off offset:-1024
	global_load_dwordx4 v[96:99], v[214:215], off offset:-1024
	global_load_dwordx4 v[100:103], v[216:217], off offset:-1024
	global_load_dwordx4 v[104:107], v[140:141], off offset:-1024
	global_load_dwordx4 v[108:111], v[186:187], off offset:-1024
	global_load_dwordx4 v[112:115], v[88:89], off
	global_load_dwordx4 v[116:119], v[214:215], off
	global_load_dwordx4 v[120:123], v[216:217], off
	global_load_dwordx4 v[124:127], v[140:141], off
	global_load_dwordx4 v[128:131], v[186:187], off
	global_load_dwordx4 v[132:135], v[88:89], off offset:1024
	global_load_dwordx4 v[136:139], v[214:215], off offset:1024
	s_waitcnt vmcnt(25)
	v_mfma_f32_32x32x16_bf16 v[50:65], v[146:149], v[142:145], v[50:65]
	global_load_dwordx4 v[146:149], v[216:217], off offset:1024
	s_waitcnt vmcnt(25)
	v_mfma_f32_32x32x16_bf16 v[34:49], v[150:153], v[142:145], v[34:49]
	global_load_dwordx4 v[150:153], v[140:141], off offset:1024
	s_waitcnt vmcnt(25)
	v_mfma_f32_32x32x16_bf16 v[18:33], v[154:157], v[142:145], v[18:33]
	global_load_dwordx4 v[154:157], v[186:187], off offset:1024
	s_waitcnt vmcnt(25)
	v_mfma_f32_32x32x16_bf16 v[2:17], v[158:161], v[142:145], v[2:17]
	global_load_dwordx4 v[158:161], v[88:89], off offset:2048
	global_load_dwordx4 v[142:145], v[214:215], off offset:2048
	s_waitcnt vmcnt(25)
	v_mfma_f32_32x32x16_bf16 v[50:65], v[166:169], v[162:165], v[50:65]
	global_load_dwordx4 v[166:169], v[216:217], off offset:2048
	s_waitcnt vmcnt(25)
	v_mfma_f32_32x32x16_bf16 v[34:49], v[170:173], v[162:165], v[34:49]
	global_load_dwordx4 v[170:173], v[140:141], off offset:2048
	s_waitcnt vmcnt(25)
	v_mfma_f32_32x32x16_bf16 v[18:33], v[174:177], v[162:165], v[18:33]
	global_load_dwordx4 v[174:177], v[186:187], off offset:2048
	s_waitcnt vmcnt(25)
	v_mfma_f32_32x32x16_bf16 v[2:17], v[178:181], v[162:165], v[2:17]
	global_load_dwordx4 v[178:181], v[88:89], off offset:3072
	global_load_dwordx4 v[162:165], v[214:215], off offset:3072
	s_waitcnt vmcnt(25)
	v_mfma_f32_32x32x16_bf16 v[50:65], v[190:193], v[182:185], v[50:65]
	global_load_dwordx4 v[190:193], v[216:217], off offset:3072
	s_waitcnt vmcnt(25)
	v_mfma_f32_32x32x16_bf16 v[34:49], v[194:197], v[182:185], v[34:49]
	global_load_dwordx4 v[194:197], v[140:141], off offset:3072
	s_waitcnt vmcnt(25)
	v_mfma_f32_32x32x16_bf16 v[18:33], v[198:201], v[182:185], v[18:33]
	global_load_dwordx4 v[198:201], v[186:187], off offset:3072
	s_waitcnt vmcnt(25)
	v_mfma_f32_32x32x16_bf16 v[2:17], v[202:205], v[182:185], v[2:17]
	v_lshl_add_u64 v[88:89], v[88:89], 0, s[20:21]
	v_lshl_add_u64 v[214:215], v[214:215], 0, s[20:21]
	v_lshl_add_u64 v[216:217], v[216:217], 0, s[20:21]
	v_lshl_add_u64 v[140:141], v[140:141], 0, s[20:21]
	v_lshl_add_u64 v[186:187], v[186:187], 0, s[20:21]
	global_load_dwordx4 v[202:205], v[88:89], off offset:-4096
	global_load_dwordx4 v[182:185], v[214:215], off offset:-4096
	s_waitcnt vmcnt(25)
	v_mfma_f32_32x32x16_bf16 v[50:65], v[96:99], v[206:209], v[50:65]
	global_load_dwordx4 v[96:99], v[216:217], off offset:-4096
	s_waitcnt vmcnt(25)
	v_mfma_f32_32x32x16_bf16 v[34:49], v[100:103], v[206:209], v[34:49]
	global_load_dwordx4 v[100:103], v[140:141], off offset:-4096
	s_waitcnt vmcnt(25)
	v_mfma_f32_32x32x16_bf16 v[18:33], v[104:107], v[206:209], v[18:33]
	global_load_dwordx4 v[104:107], v[186:187], off offset:-4096
	s_waitcnt vmcnt(25)
; #define GAS __attribute__((address_space(1)))
; __device__ __forceinline__ void ph_s5_out(Frame& F) {
;     ...
;         { const bf16* sb = (const bf16*)(ws + WS_SIN) + (size_t)g * 9 * 16 * 512 + ((size_t)nb * 16 * 64 + lane) * 8;
;           const bf16* wc = (const bf16*)(ws + WS_WC) + (size_t)g * 1024 * 256 + (((size_t)wave * 16) * 64 + lane) * 8;
; #pragma unroll 4
;           for (int kk = 0; kk < 16; ++kk) {
;               const bf16x8_t b = *(const GAS bf16x8_t*)(sb + 512 * kk);
; #pragma unroll
;               for (int i = 0; i < 4; ++i) { const bf16x8_t a = *(const GAS bf16x8_t*)(wc + (size_t)(8 * i) * 16 * 512 + 512 * kk); acc[i] = __builtin_amdgcn_mfma_f32_32x32x16_bf16(a, b, acc[i], 0, 0, 0); }
;           } }
;         if (valid) {
	v_mfma_f32_32x32x16_bf16 v[2:17], v[108:111], v[206:209], v[2:17]
	global_load_dwordx4 v[108:111], v[88:89], off offset:-3072
	global_load_dwordx4 v[206:209], v[214:215], off offset:-3072
	s_waitcnt vmcnt(25)
	v_mfma_f32_32x32x16_bf16 v[50:65], v[116:119], v[112:115], v[50:65]
	global_load_dwordx4 v[116:119], v[216:217], off offset:-3072
	s_waitcnt vmcnt(25)
	v_mfma_f32_32x32x16_bf16 v[34:49], v[120:123], v[112:115], v[34:49]
	global_load_dwordx4 v[120:123], v[140:141], off offset:-3072
	s_waitcnt vmcnt(25)
	v_mfma_f32_32x32x16_bf16 v[18:33], v[124:127], v[112:115], v[18:33]
	global_load_dwordx4 v[124:127], v[186:187], off offset:-3072
	s_waitcnt vmcnt(25)
	v_mfma_f32_32x32x16_bf16 v[2:17], v[128:131], v[112:115], v[2:17]
	global_load_dwordx4 v[128:131], v[88:89], off offset:-2048
	global_load_dwordx4 v[112:115], v[214:215], off offset:-2048
	s_waitcnt vmcnt(25)
	v_mfma_f32_32x32x16_bf16 v[50:65], v[136:139], v[132:135], v[50:65]
	global_load_dwordx4 v[136:139], v[216:217], off offset:-2048
	s_waitcnt vmcnt(25)
	v_mfma_f32_32x32x16_bf16 v[34:49], v[146:149], v[132:135], v[34:49]
	global_load_dwordx4 v[146:149], v[140:141], off offset:-2048
	s_waitcnt vmcnt(25)
	v_mfma_f32_32x32x16_bf16 v[18:33], v[150:153], v[132:135], v[18:33]
	global_load_dwordx4 v[150:153], v[186:187], off offset:-2048
	s_waitcnt vmcnt(25)
	v_mfma_f32_32x32x16_bf16 v[2:17], v[154:157], v[132:135], v[2:17]
	global_load_dwordx4 v[154:157], v[88:89], off offset:-1024
	global_load_dwordx4 v[132:135], v[214:215], off offset:-1024
	s_waitcnt vmcnt(25)
	v_mfma_f32_32x32x16_bf16 v[50:65], v[142:145], v[158:161], v[50:65]
	global_load_dwordx4 v[142:145], v[216:217], off offset:-1024
	s_waitcnt vmcnt(25)
	v_mfma_f32_32x32x16_bf16 v[34:49], v[166:169], v[158:161], v[34:49]
	global_load_dwordx4 v[166:169], v[140:141], off offset:-1024
	s_waitcnt vmcnt(25)
	v_mfma_f32_32x32x16_bf16 v[18:33], v[170:173], v[158:161], v[18:33]
	global_load_dwordx4 v[170:173], v[186:187], off offset:-1024
	s_waitcnt vmcnt(25)
	v_mfma_f32_32x32x16_bf16 v[2:17], v[174:177], v[158:161], v[2:17]
	global_load_dwordx4 v[174:177], v[88:89], off
	global_load_dwordx4 v[158:161], v[214:215], off
	s_waitcnt vmcnt(25)
	v_mfma_f32_32x32x16_bf16 v[50:65], v[162:165], v[178:181], v[50:65]
	global_load_dwordx4 v[162:165], v[216:217], off
	s_waitcnt vmcnt(25)
	v_mfma_f32_32x32x16_bf16 v[34:49], v[190:193], v[178:181], v[34:49]
	global_load_dwordx4 v[190:193], v[140:141], off
	s_waitcnt vmcnt(25)
	v_mfma_f32_32x32x16_bf16 v[18:33], v[194:197], v[178:181], v[18:33]
	global_load_dwordx4 v[194:197], v[186:187], off
	s_waitcnt vmcnt(25)
	v_mfma_f32_32x32x16_bf16 v[2:17], v[198:201], v[178:181], v[2:17]
	global_load_dwordx4 v[198:201], v[88:89], off offset:1024
	global_load_dwordx4 v[178:181], v[214:215], off offset:1024
	s_waitcnt vmcnt(25)
	v_mfma_f32_32x32x16_bf16 v[50:65], v[182:185], v[202:205], v[50:65]
	global_load_dwordx4 v[182:185], v[216:217], off offset:1024
	s_waitcnt vmcnt(25)
	v_mfma_f32_32x32x16_bf16 v[34:49], v[96:99], v[202:205], v[34:49]
	global_load_dwordx4 v[96:99], v[140:141], off offset:1024
	s_waitcnt vmcnt(25)
	v_mfma_f32_32x32x16_bf16 v[18:33], v[100:103], v[202:205], v[18:33]
	global_load_dwordx4 v[100:103], v[186:187], off offset:1024
	s_waitcnt vmcnt(25)
	v_mfma_f32_32x32x16_bf16 v[2:17], v[104:107], v[202:205], v[2:17]
	global_load_dwordx4 v[104:107], v[88:89], off offset:2048
	global_load_dwordx4 v[202:205], v[214:215], off offset:2048
	s_waitcnt vmcnt(25)
	v_mfma_f32_32x32x16_bf16 v[50:65], v[206:209], v[108:111], v[50:65]
	global_load_dwordx4 v[206:209], v[216:217], off offset:2048
	s_waitcnt vmcnt(25)
	v_mfma_f32_32x32x16_bf16 v[34:49], v[116:119], v[108:111], v[34:49]
	global_load_dwordx4 v[116:119], v[140:141], off offset:2048
	s_waitcnt vmcnt(25)
	v_mfma_f32_32x32x16_bf16 v[18:33], v[120:123], v[108:111], v[18:33]
	global_load_dwordx4 v[120:123], v[186:187], off offset:2048
	s_waitcnt vmcnt(25)
	v_mfma_f32_32x32x16_bf16 v[2:17], v[124:127], v[108:111], v[2:17]
	global_load_dwordx4 v[124:127], v[88:89], off offset:3072
	global_load_dwordx4 v[108:111], v[214:215], off offset:3072
	s_waitcnt vmcnt(25)
	v_mfma_f32_32x32x16_bf16 v[50:65], v[112:115], v[128:131], v[50:65]
	global_load_dwordx4 v[112:115], v[216:217], off offset:3072
	s_waitcnt vmcnt(25)
	v_mfma_f32_32x32x16_bf16 v[34:49], v[136:139], v[128:131], v[34:49]
	global_load_dwordx4 v[136:139], v[140:141], off offset:3072
	s_waitcnt vmcnt(25)
	v_mfma_f32_32x32x16_bf16 v[18:33], v[146:149], v[128:131], v[18:33]
	global_load_dwordx4 v[146:149], v[186:187], off offset:3072
	s_waitcnt vmcnt(25)
	v_mfma_f32_32x32x16_bf16 v[2:17], v[150:153], v[128:131], v[2:17]
	s_waitcnt vmcnt(23)
	v_mfma_f32_32x32x16_bf16 v[50:65], v[132:135], v[154:157], v[50:65]
	s_waitcnt vmcnt(22)
	v_mfma_f32_32x32x16_bf16 v[34:49], v[142:145], v[154:157], v[34:49]
	s_waitcnt vmcnt(21)
	v_mfma_f32_32x32x16_bf16 v[18:33], v[166:169], v[154:157], v[18:33]
	s_waitcnt vmcnt(20)
	v_mfma_f32_32x32x16_bf16 v[2:17], v[170:173], v[154:157], v[2:17]
	s_waitcnt vmcnt(18)
	v_mfma_f32_32x32x16_bf16 v[50:65], v[158:161], v[174:177], v[50:65]
	s_waitcnt vmcnt(17)
	v_mfma_f32_32x32x16_bf16 v[34:49], v[162:165], v[174:177], v[34:49]
	s_waitcnt vmcnt(16)
	v_mfma_f32_32x32x16_bf16 v[18:33], v[190:193], v[174:177], v[18:33]
	s_waitcnt vmcnt(15)
	v_mfma_f32_32x32x16_bf16 v[2:17], v[194:197], v[174:177], v[2:17]
	s_waitcnt vmcnt(13)
	v_mfma_f32_32x32x16_bf16 v[50:65], v[178:181], v[198:201], v[50:65]
	s_waitcnt vmcnt(12)
	v_mfma_f32_32x32x16_bf16 v[34:49], v[182:185], v[198:201], v[34:49]
	s_waitcnt vmcnt(11)
	v_mfma_f32_32x32x16_bf16 v[18:33], v[96:99], v[198:201], v[18:33]
	s_waitcnt vmcnt(10)
	v_mfma_f32_32x32x16_bf16 v[2:17], v[100:103], v[198:201], v[2:17]
	s_waitcnt vmcnt(8)
	v_mfma_f32_32x32x16_bf16 v[50:65], v[202:205], v[104:107], v[50:65]
	s_waitcnt vmcnt(7)
	v_mfma_f32_32x32x16_bf16 v[34:49], v[206:209], v[104:107], v[34:49]
	s_waitcnt vmcnt(6)
	v_mfma_f32_32x32x16_bf16 v[18:33], v[116:119], v[104:107], v[18:33]
	s_waitcnt vmcnt(5)
	v_mfma_f32_32x32x16_bf16 v[2:17], v[120:123], v[104:107], v[2:17]
	s_waitcnt vmcnt(3)
	v_mfma_f32_32x32x16_bf16 v[50:65], v[108:111], v[124:127], v[50:65]
	s_waitcnt vmcnt(2)
	v_mfma_f32_32x32x16_bf16 v[34:49], v[112:115], v[124:127], v[34:49]
	s_waitcnt vmcnt(1)
	v_mfma_f32_32x32x16_bf16 v[18:33], v[136:139], v[124:127], v[18:33]
	s_waitcnt vmcnt(0)
	v_mfma_f32_32x32x16_bf16 v[2:17], v[146:149], v[124:127], v[2:17]
	v_lshl_or_b32 v82, s24, 5, v1
	v_cmp_gt_i32_e32 vcc, s45, v82
	s_and_saveexec_b64 s[24:25], vcc
	s_cbranch_execz .LBB0_963
; #define GAS __attribute__((address_space(1)))
; __device__ __forceinline__ unsigned pk2(float lo, float hi) { const f32x2cv v = {lo, hi}; return __builtin_bit_cast(unsigned, __builtin_convertvector(v, bf16x2cv)); }
; __device__ __forceinline__ float gelu_tanh(float x) { const float u = 0.7978845608028654f * (x + 0.044715f * x * x * x); return x * __builtin_amdgcn_rcpf(1.0f + __builtin_amdgcn_exp2f(-2.8853900817779268f * u)); }
; __device__ __forceinline__ void ph_s5_out(Frame& F) {
;     ...
;         if (valid) {
;             const float* dsk = inp(F, 24) + 16 * g;
; #pragma unroll
;             for (int i = 0; i < 4; ++i)
; #pragma unroll
;                 for (int k = 0; k < 4; ++k) { const int tloc = 2 * (wave + 8 * i) + (k >> 1), p0 = 8 * (k & 1) + 4 * hh; const size_t m = (size_t)chunk * 64 + tloc;
;                     const v2u uw = *(const GAS v2u*)((chunk < 256 ? (const bf16*)(ws + WS_UG) : (const bf16*)(ws + WS_UGC)) + ug_index(g, (int)m, p0));
;                     const float y0 = gelu_tanh(acc[i][4 * k] + dsk[p0] * bflo(uw.x)), y1 = gelu_tanh(acc[i][4 * k + 1] + dsk[p0 + 1] * bfhi(uw.x));
;                     const float y2 = gelu_tanh(acc[i][4 * k + 2] + dsk[p0 + 2] * bflo(uw.y)), y3 = gelu_tanh(acc[i][4 * k + 3] + dsk[p0 + 3] * bfhi(uw.y));
;                     v2u zw; zw.x = pk2(y0, y1); zw.y = pk2(y2, y3);
;                     *(GAS v2u*)((bf16*)(ws + WS_Z) + m * 512 + 16 * g + p0) = zw; }
	v_mov_b32_e32 v68, s46
	ds_read_b64 v[84:85], v68
	v_ashrrev_i32_e32 v83, 31, v82
	v_lshlrev_b64 v[88:89], 6, v[82:83]
	v_cmp_gt_i32_e32 vcc, s47, v82
	v_lshl_add_u64 v[102:103], v[88:89], 0, s[4:5]
	v_ashrrev_i32_e32 v83, 11, v102
	v_cndmask_b32_e32 v68, v94, v95, vcc
	v_lshl_add_u64 v[86:87], v[70:71], 0, v[68:69]
	v_ashrrev_i32_e32 v68, 6, v102
	v_add_u32_e32 v83, s30, v83
	v_mov_b32_e32 v96, s26
	v_cmp_gt_i32_e32 vcc, s47, v68
	s_lshl_b32 s28, s26, 4
	s_waitcnt lgkmcnt(0)
	v_readfirstlane_b32 s27, v84
	v_and_b32_e32 v97, 31, v68
	v_cndmask_b32_e32 v84, v96, v83, vcc
	s_ashr_i32 s29, s28, 31
	v_readfirstlane_b32 s31, v85
	v_or_b32_e32 v82, v97, v67
	v_ashrrev_i32_e32 v85, 31, v84
	v_lshlrev_b32_e32 v68, 6, v102
	s_lshl_b64 s[34:35], s[28:29], 2
	v_and_b32_e32 v68, 0xf80, v68
	v_ashrrev_i32_e32 v83, 31, v82
	v_lshlrev_b64 v[84:85], 16, v[84:85]
	v_lshl_add_u64 v[82:83], v[68:69], 0, v[82:83]
	v_lshl_add_u64 v[104:105], v[86:87], 0, v[84:85]
	s_add_u32 s26, s27, s34
	v_lshl_add_u64 v[82:83], v[82:83], 4, v[104:105]
	s_addc_u32 s27, s31, s35
	v_lshl_add_u64 v[98:99], v[188:189], 2, s[26:27]
	global_load_dwordx4 v[174:177], v[98:99], off
	global_load_dwordx4 v[178:181], v[98:99], off offset:32
	global_load_dwordx2 v[142:143], v[82:83], off
	global_load_dwordx2 v[144:145], v[82:83], off offset:512
	global_load_dwordx2 v[146:147], v[82:83], off offset:1024
	global_load_dwordx2 v[148:149], v[82:83], off offset:1536
	v_lshl_add_u64 v[82:83], v[82:83], 0, s[22:23]
	global_load_dwordx2 v[150:151], v[82:83], off
	global_load_dwordx2 v[152:153], v[82:83], off offset:512
	global_load_dwordx2 v[154:155], v[82:83], off offset:1024
	global_load_dwordx2 v[156:157], v[82:83], off offset:1536
	v_lshl_add_u64 v[82:83], v[82:83], 0, s[22:23]
	global_load_dwordx2 v[158:159], v[82:83], off
	global_load_dwordx2 v[160:161], v[82:83], off offset:512
	global_load_dwordx2 v[162:163], v[82:83], off offset:1024
	global_load_dwordx2 v[164:165], v[82:83], off offset:1536
	v_lshl_add_u64 v[82:83], v[82:83], 0, s[22:23]
	global_load_dwordx2 v[166:167], v[82:83], off
	global_load_dwordx2 v[168:169], v[82:83], off offset:512
	global_load_dwordx2 v[170:171], v[82:83], off offset:1024
	global_load_dwordx2 v[172:173], v[82:83], off offset:1536
	s_lshl_b64 s[26:27], s[28:29], 1
	s_add_u32 s26, s38, s26
	v_lshlrev_b64 v[102:103], 10, v[102:103]
	s_addc_u32 s27, s39, s27
	v_lshlrev_b64 v[84:85], 1, v[188:189]
	v_lshl_add_u64 v[102:103], s[26:27], 0, v[102:103]
	v_lshl_add_u64 v[102:103], v[102:103], 0, v[84:85]
	s_mov_b32 s26, 0x3d372713
	s_mov_b32 s28, 0x3f4c422a
	s_mov_b32 s34, 0xc038aa3b
	s_waitcnt vmcnt(15)
	v_lshlrev_b32_e32 v182, 16, v142
	v_and_b32_e32 v183, 0xffff0000, v142
	v_lshlrev_b32_e32 v184, 16, v143
	v_and_b32_e32 v185, 0xffff0000, v143
	v_pk_fma_f32 v[194:195], v[174:175], v[182:183], v[50:51]
	v_pk_fma_f32 v[196:197], v[176:177], v[184:185], v[52:53]
	v_pk_mul_f32 v[190:191], v[194:195], s[26:27] op_sel_hi:[1,0]
	v_pk_mul_f32 v[192:193], v[196:197], s[26:27] op_sel_hi:[1,0]
	v_pk_mul_f32 v[190:191], v[194:195], v[190:191]
	v_pk_mul_f32 v[192:193], v[196:197], v[192:193]
	v_pk_fma_f32 v[190:191], v[194:195], v[190:191], v[194:195]
	v_pk_fma_f32 v[192:193], v[196:197], v[192:193], v[196:197]
	v_pk_mul_f32 v[190:191], v[190:191], s[28:29] op_sel_hi:[1,0]
	v_pk_mul_f32 v[192:193], v[192:193], s[28:29] op_sel_hi:[1,0]
	v_pk_mul_f32 v[190:191], v[190:191], s[34:35] op_sel_hi:[1,0]
	v_pk_mul_f32 v[192:193], v[192:193], s[34:35] op_sel_hi:[1,0]
	v_exp_f32_e32 v190, v190
	v_exp_f32_e32 v191, v191
	v_exp_f32_e32 v192, v192
	v_exp_f32_e32 v193, v193
	v_pk_add_f32 v[190:191], v[190:191], 1.0 op_sel_hi:[1,0]
	v_pk_add_f32 v[192:193], v[192:193], 1.0 op_sel_hi:[1,0]
	v_rcp_f32_e32 v190, v190
	v_rcp_f32_e32 v191, v191
	v_rcp_f32_e32 v192, v192
	v_rcp_f32_e32 v193, v193
	v_pk_mul_f32 v[194:195], v[194:195], v[190:191]
	v_pk_mul_f32 v[196:197], v[196:197], v[192:193]
	v_cvt_pk_bf16_f32 v194, v194, v195
	v_cvt_pk_bf16_f32 v195, v196, v197
	global_store_dwordx2 v[102:103], v[194:195], off
	s_waitcnt vmcnt(15)
	v_lshlrev_b32_e32 v182, 16, v144
	v_and_b32_e32 v183, 0xffff0000, v144
	v_lshlrev_b32_e32 v184, 16, v145
	v_and_b32_e32 v185, 0xffff0000, v145
	v_pk_fma_f32 v[194:195], v[178:179], v[182:183], v[54:55]
	v_pk_fma_f32 v[196:197], v[180:181], v[184:185], v[56:57]
	v_pk_mul_f32 v[190:191], v[194:195], s[26:27] op_sel_hi:[1,0]
	v_pk_mul_f32 v[192:193], v[196:197], s[26:27] op_sel_hi:[1,0]
	v_pk_mul_f32 v[190:191], v[194:195], v[190:191]
	v_pk_mul_f32 v[192:193], v[196:197], v[192:193]
	v_pk_fma_f32 v[190:191], v[194:195], v[190:191], v[194:195]
	v_pk_fma_f32 v[192:193], v[196:197], v[192:193], v[196:197]
	v_pk_mul_f32 v[190:191], v[190:191], s[28:29] op_sel_hi:[1,0]
	v_pk_mul_f32 v[192:193], v[192:193], s[28:29] op_sel_hi:[1,0]
	v_pk_mul_f32 v[190:191], v[190:191], s[34:35] op_sel_hi:[1,0]
	v_pk_mul_f32 v[192:193], v[192:193], s[34:35] op_sel_hi:[1,0]
	v_exp_f32_e32 v190, v190
	v_exp_f32_e32 v191, v191
	v_exp_f32_e32 v192, v192
	v_exp_f32_e32 v193, v193
	v_pk_add_f32 v[190:191], v[190:191], 1.0 op_sel_hi:[1,0]
	v_pk_add_f32 v[192:193], v[192:193], 1.0 op_sel_hi:[1,0]
	v_rcp_f32_e32 v190, v190
	v_rcp_f32_e32 v191, v191
	v_rcp_f32_e32 v192, v192
	v_rcp_f32_e32 v193, v193
	v_pk_mul_f32 v[194:195], v[194:195], v[190:191]
	v_pk_mul_f32 v[196:197], v[196:197], v[192:193]
	v_cvt_pk_bf16_f32 v194, v194, v195
	v_cvt_pk_bf16_f32 v195, v196, v197
	global_store_dwordx2 v[102:103], v[194:195], off offset:16
	s_waitcnt vmcnt(15)
; #define GAS __attribute__((address_space(1)))
; __device__ __forceinline__ unsigned pk2(float lo, float hi) { const f32x2cv v = {lo, hi}; return __builtin_bit_cast(unsigned, __builtin_convertvector(v, bf16x2cv)); }
; __device__ __forceinline__ float gelu_tanh(float x) { const float u = 0.7978845608028654f * (x + 0.044715f * x * x * x); return x * __builtin_amdgcn_rcpf(1.0f + __builtin_amdgcn_exp2f(-2.8853900817779268f * u)); }
; __device__ __forceinline__ void ph_s5_out(Frame& F) {
;     ...
;                 for (int k = 0; k < 4; ++k) { const int tloc = 2 * (wave + 8 * i) + (k >> 1), p0 = 8 * (k & 1) + 4 * hh; const size_t m = (size_t)chunk * 64 + tloc;
;                     const v2u uw = *(const GAS v2u*)((chunk < 256 ? (const bf16*)(ws + WS_UG) : (const bf16*)(ws + WS_UGC)) + ug_index(g, (int)m, p0));
;                     const float y0 = gelu_tanh(acc[i][4 * k] + dsk[p0] * bflo(uw.x)), y1 = gelu_tanh(acc[i][4 * k + 1] + dsk[p0 + 1] * bfhi(uw.x));
;                     const float y2 = gelu_tanh(acc[i][4 * k + 2] + dsk[p0 + 2] * bflo(uw.y)), y3 = gelu_tanh(acc[i][4 * k + 3] + dsk[p0 + 3] * bfhi(uw.y));
;                     v2u zw; zw.x = pk2(y0, y1); zw.y = pk2(y2, y3);
;                     *(GAS v2u*)((bf16*)(ws + WS_Z) + m * 512 + 16 * g + p0) = zw; }
	v_lshlrev_b32_e32 v182, 16, v146
	v_and_b32_e32 v183, 0xffff0000, v146
	v_lshlrev_b32_e32 v184, 16, v147
	v_and_b32_e32 v185, 0xffff0000, v147
	v_pk_fma_f32 v[194:195], v[174:175], v[182:183], v[58:59]
	v_pk_fma_f32 v[196:197], v[176:177], v[184:185], v[60:61]
	v_pk_mul_f32 v[190:191], v[194:195], s[26:27] op_sel_hi:[1,0]
	v_pk_mul_f32 v[192:193], v[196:197], s[26:27] op_sel_hi:[1,0]
	v_pk_mul_f32 v[190:191], v[194:195], v[190:191]
	v_pk_mul_f32 v[192:193], v[196:197], v[192:193]
	v_pk_fma_f32 v[190:191], v[194:195], v[190:191], v[194:195]
	v_pk_fma_f32 v[192:193], v[196:197], v[192:193], v[196:197]
	v_pk_mul_f32 v[190:191], v[190:191], s[28:29] op_sel_hi:[1,0]
	v_pk_mul_f32 v[192:193], v[192:193], s[28:29] op_sel_hi:[1,0]
	v_pk_mul_f32 v[190:191], v[190:191], s[34:35] op_sel_hi:[1,0]
	v_pk_mul_f32 v[192:193], v[192:193], s[34:35] op_sel_hi:[1,0]
	v_exp_f32_e32 v190, v190
	v_exp_f32_e32 v191, v191
	v_exp_f32_e32 v192, v192
	v_exp_f32_e32 v193, v193
	v_pk_add_f32 v[190:191], v[190:191], 1.0 op_sel_hi:[1,0]
	v_pk_add_f32 v[192:193], v[192:193], 1.0 op_sel_hi:[1,0]
	v_rcp_f32_e32 v190, v190
	v_rcp_f32_e32 v191, v191
	v_rcp_f32_e32 v192, v192
	v_rcp_f32_e32 v193, v193
	v_pk_mul_f32 v[194:195], v[194:195], v[190:191]
	v_pk_mul_f32 v[196:197], v[196:197], v[192:193]
	v_cvt_pk_bf16_f32 v194, v194, v195
	v_cvt_pk_bf16_f32 v195, v196, v197
	global_store_dwordx2 v[102:103], v[194:195], off offset:1024
	s_waitcnt vmcnt(15)
	v_lshlrev_b32_e32 v182, 16, v148
	v_and_b32_e32 v183, 0xffff0000, v148
	v_lshlrev_b32_e32 v184, 16, v149
	v_and_b32_e32 v185, 0xffff0000, v149
	v_pk_fma_f32 v[194:195], v[178:179], v[182:183], v[62:63]
	v_pk_fma_f32 v[196:197], v[180:181], v[184:185], v[64:65]
	v_pk_mul_f32 v[190:191], v[194:195], s[26:27] op_sel_hi:[1,0]
	v_pk_mul_f32 v[192:193], v[196:197], s[26:27] op_sel_hi:[1,0]
	v_pk_mul_f32 v[190:191], v[194:195], v[190:191]
	v_pk_mul_f32 v[192:193], v[196:197], v[192:193]
	v_pk_fma_f32 v[190:191], v[194:195], v[190:191], v[194:195]
	v_pk_fma_f32 v[192:193], v[196:197], v[192:193], v[196:197]
	v_pk_mul_f32 v[190:191], v[190:191], s[28:29] op_sel_hi:[1,0]
	v_pk_mul_f32 v[192:193], v[192:193], s[28:29] op_sel_hi:[1,0]
	v_pk_mul_f32 v[190:191], v[190:191], s[34:35] op_sel_hi:[1,0]
	v_pk_mul_f32 v[192:193], v[192:193], s[34:35] op_sel_hi:[1,0]
	v_exp_f32_e32 v190, v190
	v_exp_f32_e32 v191, v191
	v_exp_f32_e32 v192, v192
	v_exp_f32_e32 v193, v193
	v_pk_add_f32 v[190:191], v[190:191], 1.0 op_sel_hi:[1,0]
	v_pk_add_f32 v[192:193], v[192:193], 1.0 op_sel_hi:[1,0]
	v_rcp_f32_e32 v190, v190
	v_rcp_f32_e32 v191, v191
	v_rcp_f32_e32 v192, v192
	v_rcp_f32_e32 v193, v193
	v_pk_mul_f32 v[194:195], v[194:195], v[190:191]
	v_pk_mul_f32 v[196:197], v[196:197], v[192:193]
	v_cvt_pk_bf16_f32 v194, v194, v195
	v_cvt_pk_bf16_f32 v195, v196, v197
	global_store_dwordx2 v[102:103], v[194:195], off offset:1040
	v_lshl_add_u64 v[102:103], v[102:103], 0, s[22:23]
	s_waitcnt vmcnt(15)
	v_lshlrev_b32_e32 v182, 16, v150
	v_and_b32_e32 v183, 0xffff0000, v150
	v_lshlrev_b32_e32 v184, 16, v151
	v_and_b32_e32 v185, 0xffff0000, v151
	v_pk_fma_f32 v[194:195], v[174:175], v[182:183], v[34:35]
	v_pk_fma_f32 v[196:197], v[176:177], v[184:185], v[36:37]
	v_pk_mul_f32 v[190:191], v[194:195], s[26:27] op_sel_hi:[1,0]
	v_pk_mul_f32 v[192:193], v[196:197], s[26:27] op_sel_hi:[1,0]
	v_pk_mul_f32 v[190:191], v[194:195], v[190:191]
	v_pk_mul_f32 v[192:193], v[196:197], v[192:193]
	v_pk_fma_f32 v[190:191], v[194:195], v[190:191], v[194:195]
	v_pk_fma_f32 v[192:193], v[196:197], v[192:193], v[196:197]
	v_pk_mul_f32 v[190:191], v[190:191], s[28:29] op_sel_hi:[1,0]
	v_pk_mul_f32 v[192:193], v[192:193], s[28:29] op_sel_hi:[1,0]
	v_pk_mul_f32 v[190:191], v[190:191], s[34:35] op_sel_hi:[1,0]
	v_pk_mul_f32 v[192:193], v[192:193], s[34:35] op_sel_hi:[1,0]
	v_exp_f32_e32 v190, v190
	v_exp_f32_e32 v191, v191
	v_exp_f32_e32 v192, v192
	v_exp_f32_e32 v193, v193
	v_pk_add_f32 v[190:191], v[190:191], 1.0 op_sel_hi:[1,0]
	v_pk_add_f32 v[192:193], v[192:193], 1.0 op_sel_hi:[1,0]
	v_rcp_f32_e32 v190, v190
	v_rcp_f32_e32 v191, v191
	v_rcp_f32_e32 v192, v192
	v_rcp_f32_e32 v193, v193
	v_pk_mul_f32 v[194:195], v[194:195], v[190:191]
	v_pk_mul_f32 v[196:197], v[196:197], v[192:193]
	v_cvt_pk_bf16_f32 v194, v194, v195
	v_cvt_pk_bf16_f32 v195, v196, v197
	global_store_dwordx2 v[102:103], v[194:195], off
	s_waitcnt vmcnt(15)
	v_lshlrev_b32_e32 v182, 16, v152
	v_and_b32_e32 v183, 0xffff0000, v152
	v_lshlrev_b32_e32 v184, 16, v153
	v_and_b32_e32 v185, 0xffff0000, v153
	v_pk_fma_f32 v[194:195], v[178:179], v[182:183], v[38:39]
	v_pk_fma_f32 v[196:197], v[180:181], v[184:185], v[40:41]
	v_pk_mul_f32 v[190:191], v[194:195], s[26:27] op_sel_hi:[1,0]
	v_pk_mul_f32 v[192:193], v[196:197], s[26:27] op_sel_hi:[1,0]
	v_pk_mul_f32 v[190:191], v[194:195], v[190:191]
	v_pk_mul_f32 v[192:193], v[196:197], v[192:193]
	v_pk_fma_f32 v[190:191], v[194:195], v[190:191], v[194:195]
	v_pk_fma_f32 v[192:193], v[196:197], v[192:193], v[196:197]
	v_pk_mul_f32 v[190:191], v[190:191], s[28:29] op_sel_hi:[1,0]
	v_pk_mul_f32 v[192:193], v[192:193], s[28:29] op_sel_hi:[1,0]
	v_pk_mul_f32 v[190:191], v[190:191], s[34:35] op_sel_hi:[1,0]
	v_pk_mul_f32 v[192:193], v[192:193], s[34:35] op_sel_hi:[1,0]
	v_exp_f32_e32 v190, v190
	v_exp_f32_e32 v191, v191
	v_exp_f32_e32 v192, v192
	v_exp_f32_e32 v193, v193
	v_pk_add_f32 v[190:191], v[190:191], 1.0 op_sel_hi:[1,0]
	v_pk_add_f32 v[192:193], v[192:193], 1.0 op_sel_hi:[1,0]
	v_rcp_f32_e32 v190, v190
	v_rcp_f32_e32 v191, v191
	v_rcp_f32_e32 v192, v192
	v_rcp_f32_e32 v193, v193
	v_pk_mul_f32 v[194:195], v[194:195], v[190:191]
	v_pk_mul_f32 v[196:197], v[196:197], v[192:193]
	v_cvt_pk_bf16_f32 v194, v194, v195
	v_cvt_pk_bf16_f32 v195, v196, v197
	global_store_dwordx2 v[102:103], v[194:195], off offset:16
	s_waitcnt vmcnt(15)
; #define GAS __attribute__((address_space(1)))
; __device__ __forceinline__ unsigned pk2(float lo, float hi) { const f32x2cv v = {lo, hi}; return __builtin_bit_cast(unsigned, __builtin_convertvector(v, bf16x2cv)); }
; __device__ __forceinline__ float gelu_tanh(float x) { const float u = 0.7978845608028654f * (x + 0.044715f * x * x * x); return x * __builtin_amdgcn_rcpf(1.0f + __builtin_amdgcn_exp2f(-2.8853900817779268f * u)); }
; __device__ __forceinline__ void ph_s5_out(Frame& F) {
;     ...
;                 for (int k = 0; k < 4; ++k) { const int tloc = 2 * (wave + 8 * i) + (k >> 1), p0 = 8 * (k & 1) + 4 * hh; const size_t m = (size_t)chunk * 64 + tloc;
;                     const v2u uw = *(const GAS v2u*)((chunk < 256 ? (const bf16*)(ws + WS_UG) : (const bf16*)(ws + WS_UGC)) + ug_index(g, (int)m, p0));
;                     const float y0 = gelu_tanh(acc[i][4 * k] + dsk[p0] * bflo(uw.x)), y1 = gelu_tanh(acc[i][4 * k + 1] + dsk[p0 + 1] * bfhi(uw.x));
;                     const float y2 = gelu_tanh(acc[i][4 * k + 2] + dsk[p0 + 2] * bflo(uw.y)), y3 = gelu_tanh(acc[i][4 * k + 3] + dsk[p0 + 3] * bfhi(uw.y));
;                     v2u zw; zw.x = pk2(y0, y1); zw.y = pk2(y2, y3);
;                     *(GAS v2u*)((bf16*)(ws + WS_Z) + m * 512 + 16 * g + p0) = zw; }
	v_lshlrev_b32_e32 v182, 16, v154
	v_and_b32_e32 v183, 0xffff0000, v154
	v_lshlrev_b32_e32 v184, 16, v155
	v_and_b32_e32 v185, 0xffff0000, v155
	v_pk_fma_f32 v[194:195], v[174:175], v[182:183], v[42:43]
	v_pk_fma_f32 v[196:197], v[176:177], v[184:185], v[44:45]
	v_pk_mul_f32 v[190:191], v[194:195], s[26:27] op_sel_hi:[1,0]
	v_pk_mul_f32 v[192:193], v[196:197], s[26:27] op_sel_hi:[1,0]
	v_pk_mul_f32 v[190:191], v[194:195], v[190:191]
	v_pk_mul_f32 v[192:193], v[196:197], v[192:193]
	v_pk_fma_f32 v[190:191], v[194:195], v[190:191], v[194:195]
	v_pk_fma_f32 v[192:193], v[196:197], v[192:193], v[196:197]
	v_pk_mul_f32 v[190:191], v[190:191], s[28:29] op_sel_hi:[1,0]
	v_pk_mul_f32 v[192:193], v[192:193], s[28:29] op_sel_hi:[1,0]
	v_pk_mul_f32 v[190:191], v[190:191], s[34:35] op_sel_hi:[1,0]
	v_pk_mul_f32 v[192:193], v[192:193], s[34:35] op_sel_hi:[1,0]
	v_exp_f32_e32 v190, v190
	v_exp_f32_e32 v191, v191
	v_exp_f32_e32 v192, v192
	v_exp_f32_e32 v193, v193
	v_pk_add_f32 v[190:191], v[190:191], 1.0 op_sel_hi:[1,0]
	v_pk_add_f32 v[192:193], v[192:193], 1.0 op_sel_hi:[1,0]
	v_rcp_f32_e32 v190, v190
	v_rcp_f32_e32 v191, v191
	v_rcp_f32_e32 v192, v192
	v_rcp_f32_e32 v193, v193
	v_pk_mul_f32 v[194:195], v[194:195], v[190:191]
	v_pk_mul_f32 v[196:197], v[196:197], v[192:193]
	v_cvt_pk_bf16_f32 v194, v194, v195
	v_cvt_pk_bf16_f32 v195, v196, v197
	global_store_dwordx2 v[102:103], v[194:195], off offset:1024
	s_waitcnt vmcnt(15)
	v_lshlrev_b32_e32 v182, 16, v156
	v_and_b32_e32 v183, 0xffff0000, v156
	v_lshlrev_b32_e32 v184, 16, v157
	v_and_b32_e32 v185, 0xffff0000, v157
	v_pk_fma_f32 v[194:195], v[178:179], v[182:183], v[46:47]
	v_pk_fma_f32 v[196:197], v[180:181], v[184:185], v[48:49]
	v_pk_mul_f32 v[190:191], v[194:195], s[26:27] op_sel_hi:[1,0]
	v_pk_mul_f32 v[192:193], v[196:197], s[26:27] op_sel_hi:[1,0]
	v_pk_mul_f32 v[190:191], v[194:195], v[190:191]
	v_pk_mul_f32 v[192:193], v[196:197], v[192:193]
	v_pk_fma_f32 v[190:191], v[194:195], v[190:191], v[194:195]
	v_pk_fma_f32 v[192:193], v[196:197], v[192:193], v[196:197]
	v_pk_mul_f32 v[190:191], v[190:191], s[28:29] op_sel_hi:[1,0]
	v_pk_mul_f32 v[192:193], v[192:193], s[28:29] op_sel_hi:[1,0]
	v_pk_mul_f32 v[190:191], v[190:191], s[34:35] op_sel_hi:[1,0]
	v_pk_mul_f32 v[192:193], v[192:193], s[34:35] op_sel_hi:[1,0]
	v_exp_f32_e32 v190, v190
	v_exp_f32_e32 v191, v191
	v_exp_f32_e32 v192, v192
	v_exp_f32_e32 v193, v193
	v_pk_add_f32 v[190:191], v[190:191], 1.0 op_sel_hi:[1,0]
	v_pk_add_f32 v[192:193], v[192:193], 1.0 op_sel_hi:[1,0]
	v_rcp_f32_e32 v190, v190
	v_rcp_f32_e32 v191, v191
	v_rcp_f32_e32 v192, v192
	v_rcp_f32_e32 v193, v193
	v_pk_mul_f32 v[194:195], v[194:195], v[190:191]
	v_pk_mul_f32 v[196:197], v[196:197], v[192:193]
	v_cvt_pk_bf16_f32 v194, v194, v195
	v_cvt_pk_bf16_f32 v195, v196, v197
	global_store_dwordx2 v[102:103], v[194:195], off offset:1040
	v_lshl_add_u64 v[102:103], v[102:103], 0, s[22:23]
	s_waitcnt vmcnt(15)
	v_lshlrev_b32_e32 v182, 16, v158
	v_and_b32_e32 v183, 0xffff0000, v158
	v_lshlrev_b32_e32 v184, 16, v159
	v_and_b32_e32 v185, 0xffff0000, v159
	v_pk_fma_f32 v[194:195], v[174:175], v[182:183], v[18:19]
	v_pk_fma_f32 v[196:197], v[176:177], v[184:185], v[20:21]
	v_pk_mul_f32 v[190:191], v[194:195], s[26:27] op_sel_hi:[1,0]
	v_pk_mul_f32 v[192:193], v[196:197], s[26:27] op_sel_hi:[1,0]
	v_pk_mul_f32 v[190:191], v[194:195], v[190:191]
	v_pk_mul_f32 v[192:193], v[196:197], v[192:193]
	v_pk_fma_f32 v[190:191], v[194:195], v[190:191], v[194:195]
	v_pk_fma_f32 v[192:193], v[196:197], v[192:193], v[196:197]
	v_pk_mul_f32 v[190:191], v[190:191], s[28:29] op_sel_hi:[1,0]
	v_pk_mul_f32 v[192:193], v[192:193], s[28:29] op_sel_hi:[1,0]
	v_pk_mul_f32 v[190:191], v[190:191], s[34:35] op_sel_hi:[1,0]
	v_pk_mul_f32 v[192:193], v[192:193], s[34:35] op_sel_hi:[1,0]
	v_exp_f32_e32 v190, v190
	v_exp_f32_e32 v191, v191
	v_exp_f32_e32 v192, v192
	v_exp_f32_e32 v193, v193
	v_pk_add_f32 v[190:191], v[190:191], 1.0 op_sel_hi:[1,0]
	v_pk_add_f32 v[192:193], v[192:193], 1.0 op_sel_hi:[1,0]
	v_rcp_f32_e32 v190, v190
	v_rcp_f32_e32 v191, v191
	v_rcp_f32_e32 v192, v192
	v_rcp_f32_e32 v193, v193
	v_pk_mul_f32 v[194:195], v[194:195], v[190:191]
	v_pk_mul_f32 v[196:197], v[196:197], v[192:193]
	v_cvt_pk_bf16_f32 v194, v194, v195
	v_cvt_pk_bf16_f32 v195, v196, v197
	global_store_dwordx2 v[102:103], v[194:195], off
	s_waitcnt vmcnt(15)
	v_lshlrev_b32_e32 v182, 16, v160
	v_and_b32_e32 v183, 0xffff0000, v160
	v_lshlrev_b32_e32 v184, 16, v161
	v_and_b32_e32 v185, 0xffff0000, v161
	v_pk_fma_f32 v[194:195], v[178:179], v[182:183], v[22:23]
	v_pk_fma_f32 v[196:197], v[180:181], v[184:185], v[24:25]
	v_pk_mul_f32 v[190:191], v[194:195], s[26:27] op_sel_hi:[1,0]
	v_pk_mul_f32 v[192:193], v[196:197], s[26:27] op_sel_hi:[1,0]
	v_pk_mul_f32 v[190:191], v[194:195], v[190:191]
	v_pk_mul_f32 v[192:193], v[196:197], v[192:193]
	v_pk_fma_f32 v[190:191], v[194:195], v[190:191], v[194:195]
	v_pk_fma_f32 v[192:193], v[196:197], v[192:193], v[196:197]
	v_pk_mul_f32 v[190:191], v[190:191], s[28:29] op_sel_hi:[1,0]
	v_pk_mul_f32 v[192:193], v[192:193], s[28:29] op_sel_hi:[1,0]
	v_pk_mul_f32 v[190:191], v[190:191], s[34:35] op_sel_hi:[1,0]
	v_pk_mul_f32 v[192:193], v[192:193], s[34:35] op_sel_hi:[1,0]
	v_exp_f32_e32 v190, v190
	v_exp_f32_e32 v191, v191
	v_exp_f32_e32 v192, v192
	v_exp_f32_e32 v193, v193
	v_pk_add_f32 v[190:191], v[190:191], 1.0 op_sel_hi:[1,0]
	v_pk_add_f32 v[192:193], v[192:193], 1.0 op_sel_hi:[1,0]
	v_rcp_f32_e32 v190, v190
	v_rcp_f32_e32 v191, v191
	v_rcp_f32_e32 v192, v192
	v_rcp_f32_e32 v193, v193
	v_pk_mul_f32 v[194:195], v[194:195], v[190:191]
	v_pk_mul_f32 v[196:197], v[196:197], v[192:193]
	v_cvt_pk_bf16_f32 v194, v194, v195
	v_cvt_pk_bf16_f32 v195, v196, v197
	global_store_dwordx2 v[102:103], v[194:195], off offset:16
	s_waitcnt vmcnt(15)
; #define GAS __attribute__((address_space(1)))
; __device__ __forceinline__ unsigned pk2(float lo, float hi) { const f32x2cv v = {lo, hi}; return __builtin_bit_cast(unsigned, __builtin_convertvector(v, bf16x2cv)); }
; __device__ __forceinline__ float gelu_tanh(float x) { const float u = 0.7978845608028654f * (x + 0.044715f * x * x * x); return x * __builtin_amdgcn_rcpf(1.0f + __builtin_amdgcn_exp2f(-2.8853900817779268f * u)); }
; __device__ __forceinline__ void ph_s5_out(Frame& F) {
;     ...
;                 for (int k = 0; k < 4; ++k) { const int tloc = 2 * (wave + 8 * i) + (k >> 1), p0 = 8 * (k & 1) + 4 * hh; const size_t m = (size_t)chunk * 64 + tloc;
;                     const v2u uw = *(const GAS v2u*)((chunk < 256 ? (const bf16*)(ws + WS_UG) : (const bf16*)(ws + WS_UGC)) + ug_index(g, (int)m, p0));
;                     const float y0 = gelu_tanh(acc[i][4 * k] + dsk[p0] * bflo(uw.x)), y1 = gelu_tanh(acc[i][4 * k + 1] + dsk[p0 + 1] * bfhi(uw.x));
;                     const float y2 = gelu_tanh(acc[i][4 * k + 2] + dsk[p0 + 2] * bflo(uw.y)), y3 = gelu_tanh(acc[i][4 * k + 3] + dsk[p0 + 3] * bfhi(uw.y));
;                     v2u zw; zw.x = pk2(y0, y1); zw.y = pk2(y2, y3);
;                     *(GAS v2u*)((bf16*)(ws + WS_Z) + m * 512 + 16 * g + p0) = zw; }
	v_lshlrev_b32_e32 v182, 16, v162
	v_and_b32_e32 v183, 0xffff0000, v162
	v_lshlrev_b32_e32 v184, 16, v163
	v_and_b32_e32 v185, 0xffff0000, v163
	v_pk_fma_f32 v[194:195], v[174:175], v[182:183], v[26:27]
	v_pk_fma_f32 v[196:197], v[176:177], v[184:185], v[28:29]
	v_pk_mul_f32 v[190:191], v[194:195], s[26:27] op_sel_hi:[1,0]
	v_pk_mul_f32 v[192:193], v[196:197], s[26:27] op_sel_hi:[1,0]
	v_pk_mul_f32 v[190:191], v[194:195], v[190:191]
	v_pk_mul_f32 v[192:193], v[196:197], v[192:193]
	v_pk_fma_f32 v[190:191], v[194:195], v[190:191], v[194:195]
	v_pk_fma_f32 v[192:193], v[196:197], v[192:193], v[196:197]
	v_pk_mul_f32 v[190:191], v[190:191], s[28:29] op_sel_hi:[1,0]
	v_pk_mul_f32 v[192:193], v[192:193], s[28:29] op_sel_hi:[1,0]
	v_pk_mul_f32 v[190:191], v[190:191], s[34:35] op_sel_hi:[1,0]
	v_pk_mul_f32 v[192:193], v[192:193], s[34:35] op_sel_hi:[1,0]
	v_exp_f32_e32 v190, v190
	v_exp_f32_e32 v191, v191
	v_exp_f32_e32 v192, v192
	v_exp_f32_e32 v193, v193
	v_pk_add_f32 v[190:191], v[190:191], 1.0 op_sel_hi:[1,0]
	v_pk_add_f32 v[192:193], v[192:193], 1.0 op_sel_hi:[1,0]
	v_rcp_f32_e32 v190, v190
	v_rcp_f32_e32 v191, v191
	v_rcp_f32_e32 v192, v192
	v_rcp_f32_e32 v193, v193
	v_pk_mul_f32 v[194:195], v[194:195], v[190:191]
	v_pk_mul_f32 v[196:197], v[196:197], v[192:193]
	v_cvt_pk_bf16_f32 v194, v194, v195
	v_cvt_pk_bf16_f32 v195, v196, v197
	global_store_dwordx2 v[102:103], v[194:195], off offset:1024
	s_waitcnt vmcnt(15)
	v_lshlrev_b32_e32 v182, 16, v164
	v_and_b32_e32 v183, 0xffff0000, v164
	v_lshlrev_b32_e32 v184, 16, v165
	v_and_b32_e32 v185, 0xffff0000, v165
	v_pk_fma_f32 v[194:195], v[178:179], v[182:183], v[30:31]
	v_pk_fma_f32 v[196:197], v[180:181], v[184:185], v[32:33]
	v_pk_mul_f32 v[190:191], v[194:195], s[26:27] op_sel_hi:[1,0]
	v_pk_mul_f32 v[192:193], v[196:197], s[26:27] op_sel_hi:[1,0]
	v_pk_mul_f32 v[190:191], v[194:195], v[190:191]
	v_pk_mul_f32 v[192:193], v[196:197], v[192:193]
	v_pk_fma_f32 v[190:191], v[194:195], v[190:191], v[194:195]
	v_pk_fma_f32 v[192:193], v[196:197], v[192:193], v[196:197]
	v_pk_mul_f32 v[190:191], v[190:191], s[28:29] op_sel_hi:[1,0]
	v_pk_mul_f32 v[192:193], v[192:193], s[28:29] op_sel_hi:[1,0]
	v_pk_mul_f32 v[190:191], v[190:191], s[34:35] op_sel_hi:[1,0]
	v_pk_mul_f32 v[192:193], v[192:193], s[34:35] op_sel_hi:[1,0]
	v_exp_f32_e32 v190, v190
	v_exp_f32_e32 v191, v191
	v_exp_f32_e32 v192, v192
	v_exp_f32_e32 v193, v193
	v_pk_add_f32 v[190:191], v[190:191], 1.0 op_sel_hi:[1,0]
	v_pk_add_f32 v[192:193], v[192:193], 1.0 op_sel_hi:[1,0]
	v_rcp_f32_e32 v190, v190
	v_rcp_f32_e32 v191, v191
	v_rcp_f32_e32 v192, v192
	v_rcp_f32_e32 v193, v193
	v_pk_mul_f32 v[194:195], v[194:195], v[190:191]
	v_pk_mul_f32 v[196:197], v[196:197], v[192:193]
	v_cvt_pk_bf16_f32 v194, v194, v195
	v_cvt_pk_bf16_f32 v195, v196, v197
	global_store_dwordx2 v[102:103], v[194:195], off offset:1040
	v_lshl_add_u64 v[102:103], v[102:103], 0, s[22:23]
	s_waitcnt vmcnt(15)
	v_lshlrev_b32_e32 v182, 16, v166
	v_and_b32_e32 v183, 0xffff0000, v166
	v_lshlrev_b32_e32 v184, 16, v167
	v_and_b32_e32 v185, 0xffff0000, v167
	v_pk_fma_f32 v[194:195], v[174:175], v[182:183], v[2:3]
	v_pk_fma_f32 v[196:197], v[176:177], v[184:185], v[4:5]
	v_pk_mul_f32 v[190:191], v[194:195], s[26:27] op_sel_hi:[1,0]
	v_pk_mul_f32 v[192:193], v[196:197], s[26:27] op_sel_hi:[1,0]
	v_pk_mul_f32 v[190:191], v[194:195], v[190:191]
	v_pk_mul_f32 v[192:193], v[196:197], v[192:193]
	v_pk_fma_f32 v[190:191], v[194:195], v[190:191], v[194:195]
	v_pk_fma_f32 v[192:193], v[196:197], v[192:193], v[196:197]
	v_pk_mul_f32 v[190:191], v[190:191], s[28:29] op_sel_hi:[1,0]
	v_pk_mul_f32 v[192:193], v[192:193], s[28:29] op_sel_hi:[1,0]
	v_pk_mul_f32 v[190:191], v[190:191], s[34:35] op_sel_hi:[1,0]
	v_pk_mul_f32 v[192:193], v[192:193], s[34:35] op_sel_hi:[1,0]
	v_exp_f32_e32 v190, v190
	v_exp_f32_e32 v191, v191
	v_exp_f32_e32 v192, v192
	v_exp_f32_e32 v193, v193
	v_pk_add_f32 v[190:191], v[190:191], 1.0 op_sel_hi:[1,0]
	v_pk_add_f32 v[192:193], v[192:193], 1.0 op_sel_hi:[1,0]
	v_rcp_f32_e32 v190, v190
	v_rcp_f32_e32 v191, v191
	v_rcp_f32_e32 v192, v192
	v_rcp_f32_e32 v193, v193
	v_pk_mul_f32 v[194:195], v[194:195], v[190:191]
	v_pk_mul_f32 v[196:197], v[196:197], v[192:193]
	v_cvt_pk_bf16_f32 v194, v194, v195
	v_cvt_pk_bf16_f32 v195, v196, v197
	global_store_dwordx2 v[102:103], v[194:195], off
	s_waitcnt vmcnt(15)
; #define GAS __attribute__((address_space(1)))
; __device__ __forceinline__ unsigned pk2(float lo, float hi) { const f32x2cv v = {lo, hi}; return __builtin_bit_cast(unsigned, __builtin_convertvector(v, bf16x2cv)); }
; __device__ __forceinline__ float gelu_tanh(float x) { const float u = 0.7978845608028654f * (x + 0.044715f * x * x * x); return x * __builtin_amdgcn_rcpf(1.0f + __builtin_amdgcn_exp2f(-2.8853900817779268f * u)); }
; __device__ __forceinline__ void ph_s5_out(Frame& F) {
;     ...
;                 for (int k = 0; k < 4; ++k) { const int tloc = 2 * (wave + 8 * i) + (k >> 1), p0 = 8 * (k & 1) + 4 * hh; const size_t m = (size_t)chunk * 64 + tloc;
;                     const v2u uw = *(const GAS v2u*)((chunk < 256 ? (const bf16*)(ws + WS_UG) : (const bf16*)(ws + WS_UGC)) + ug_index(g, (int)m, p0));
;                     const float y0 = gelu_tanh(acc[i][4 * k] + dsk[p0] * bflo(uw.x)), y1 = gelu_tanh(acc[i][4 * k + 1] + dsk[p0 + 1] * bfhi(uw.x));
;                     const float y2 = gelu_tanh(acc[i][4 * k + 2] + dsk[p0 + 2] * bflo(uw.y)), y3 = gelu_tanh(acc[i][4 * k + 3] + dsk[p0 + 3] * bfhi(uw.y));
;                     v2u zw; zw.x = pk2(y0, y1); zw.y = pk2(y2, y3);
;                     *(GAS v2u*)((bf16*)(ws + WS_Z) + m * 512 + 16 * g + p0) = zw; }
	v_lshlrev_b32_e32 v182, 16, v168
	v_and_b32_e32 v183, 0xffff0000, v168
	v_lshlrev_b32_e32 v184, 16, v169
	v_and_b32_e32 v185, 0xffff0000, v169
	v_pk_fma_f32 v[194:195], v[178:179], v[182:183], v[6:7]
	v_pk_fma_f32 v[196:197], v[180:181], v[184:185], v[8:9]
	v_pk_mul_f32 v[190:191], v[194:195], s[26:27] op_sel_hi:[1,0]
	v_pk_mul_f32 v[192:193], v[196:197], s[26:27] op_sel_hi:[1,0]
	v_pk_mul_f32 v[190:191], v[194:195], v[190:191]
	v_pk_mul_f32 v[192:193], v[196:197], v[192:193]
	v_pk_fma_f32 v[190:191], v[194:195], v[190:191], v[194:195]
	v_pk_fma_f32 v[192:193], v[196:197], v[192:193], v[196:197]
	v_pk_mul_f32 v[190:191], v[190:191], s[28:29] op_sel_hi:[1,0]
	v_pk_mul_f32 v[192:193], v[192:193], s[28:29] op_sel_hi:[1,0]
	v_pk_mul_f32 v[190:191], v[190:191], s[34:35] op_sel_hi:[1,0]
	v_pk_mul_f32 v[192:193], v[192:193], s[34:35] op_sel_hi:[1,0]
	v_exp_f32_e32 v190, v190
	v_exp_f32_e32 v191, v191
	v_exp_f32_e32 v192, v192
	v_exp_f32_e32 v193, v193
	v_pk_add_f32 v[190:191], v[190:191], 1.0 op_sel_hi:[1,0]
	v_pk_add_f32 v[192:193], v[192:193], 1.0 op_sel_hi:[1,0]
	v_rcp_f32_e32 v190, v190
	v_rcp_f32_e32 v191, v191
	v_rcp_f32_e32 v192, v192
	v_rcp_f32_e32 v193, v193
	v_pk_mul_f32 v[194:195], v[194:195], v[190:191]
	v_pk_mul_f32 v[196:197], v[196:197], v[192:193]
	v_cvt_pk_bf16_f32 v194, v194, v195
	v_cvt_pk_bf16_f32 v195, v196, v197
	global_store_dwordx2 v[102:103], v[194:195], off offset:16
	s_waitcnt vmcnt(15)
	v_lshlrev_b32_e32 v182, 16, v170
	v_and_b32_e32 v183, 0xffff0000, v170
	v_lshlrev_b32_e32 v184, 16, v171
	v_and_b32_e32 v185, 0xffff0000, v171
	v_pk_fma_f32 v[194:195], v[174:175], v[182:183], v[10:11]
	v_pk_fma_f32 v[196:197], v[176:177], v[184:185], v[12:13]
	v_pk_mul_f32 v[190:191], v[194:195], s[26:27] op_sel_hi:[1,0]
	v_pk_mul_f32 v[192:193], v[196:197], s[26:27] op_sel_hi:[1,0]
	v_pk_mul_f32 v[190:191], v[194:195], v[190:191]
	v_pk_mul_f32 v[192:193], v[196:197], v[192:193]
	v_pk_fma_f32 v[190:191], v[194:195], v[190:191], v[194:195]
	v_pk_fma_f32 v[192:193], v[196:197], v[192:193], v[196:197]
	v_pk_mul_f32 v[190:191], v[190:191], s[28:29] op_sel_hi:[1,0]
	v_pk_mul_f32 v[192:193], v[192:193], s[28:29] op_sel_hi:[1,0]
	v_pk_mul_f32 v[190:191], v[190:191], s[34:35] op_sel_hi:[1,0]
	v_pk_mul_f32 v[192:193], v[192:193], s[34:35] op_sel_hi:[1,0]
	v_exp_f32_e32 v190, v190
	v_exp_f32_e32 v191, v191
	v_exp_f32_e32 v192, v192
	v_exp_f32_e32 v193, v193
	v_pk_add_f32 v[190:191], v[190:191], 1.0 op_sel_hi:[1,0]
	v_pk_add_f32 v[192:193], v[192:193], 1.0 op_sel_hi:[1,0]
	v_rcp_f32_e32 v190, v190
	v_rcp_f32_e32 v191, v191
	v_rcp_f32_e32 v192, v192
	v_rcp_f32_e32 v193, v193
	v_pk_mul_f32 v[194:195], v[194:195], v[190:191]
	v_pk_mul_f32 v[196:197], v[196:197], v[192:193]
	v_cvt_pk_bf16_f32 v194, v194, v195
	v_cvt_pk_bf16_f32 v195, v196, v197
	global_store_dwordx2 v[102:103], v[194:195], off offset:1024
	s_waitcnt vmcnt(15)
	v_lshlrev_b32_e32 v182, 16, v172
	v_and_b32_e32 v183, 0xffff0000, v172
	v_lshlrev_b32_e32 v184, 16, v173
	v_and_b32_e32 v185, 0xffff0000, v173
	v_pk_fma_f32 v[194:195], v[178:179], v[182:183], v[14:15]
	v_pk_fma_f32 v[196:197], v[180:181], v[184:185], v[16:17]
	v_pk_mul_f32 v[190:191], v[194:195], s[26:27] op_sel_hi:[1,0]
	v_pk_mul_f32 v[192:193], v[196:197], s[26:27] op_sel_hi:[1,0]
	v_pk_mul_f32 v[190:191], v[194:195], v[190:191]
	v_pk_mul_f32 v[192:193], v[196:197], v[192:193]
	v_pk_fma_f32 v[190:191], v[194:195], v[190:191], v[194:195]
	v_pk_fma_f32 v[192:193], v[196:197], v[192:193], v[196:197]
	v_pk_mul_f32 v[190:191], v[190:191], s[28:29] op_sel_hi:[1,0]
	v_pk_mul_f32 v[192:193], v[192:193], s[28:29] op_sel_hi:[1,0]
	v_pk_mul_f32 v[190:191], v[190:191], s[34:35] op_sel_hi:[1,0]
	v_pk_mul_f32 v[192:193], v[192:193], s[34:35] op_sel_hi:[1,0]
	v_exp_f32_e32 v190, v190
	v_exp_f32_e32 v191, v191
	v_exp_f32_e32 v192, v192
	v_exp_f32_e32 v193, v193
	v_pk_add_f32 v[190:191], v[190:191], 1.0 op_sel_hi:[1,0]
	v_pk_add_f32 v[192:193], v[192:193], 1.0 op_sel_hi:[1,0]
	v_rcp_f32_e32 v190, v190
	v_rcp_f32_e32 v191, v191
	v_rcp_f32_e32 v192, v192
	v_rcp_f32_e32 v193, v193
	v_pk_mul_f32 v[194:195], v[194:195], v[190:191]
	v_pk_mul_f32 v[196:197], v[196:197], v[192:193]
	v_cvt_pk_bf16_f32 v194, v194, v195
	v_cvt_pk_bf16_f32 v195, v196, v197
	global_store_dwordx2 v[102:103], v[194:195], off offset:1040
	s_branch .LBB0_963
